# rstd-table build at the start of the up / ABI / SGI GEMM phases: removed the five redundant vmcnt(0) waits that serialized the six units' partial-sum loads (register-disjoint, checked), so all 24 load
# speedup vs baseline: 1.0108x; 1.0108x over previous
;     __host__ __device__ bool next(int i, Unit& u) const {
;         const long L = (long)i * G + c; if (L >= nwg) return false;
;         int wgid = (int)L; { const int q = nwg / NXCD, r = nwg % NXCD, xcd = wgid % NXCD, off = wgid / NXCD; wgid = (xcd < r ? xcd * (q + 1) : r * (q + 1) + (xcd - r) * q) + off; }
;         const int nig = WGM * nN, gid = wgid / nig, fm = gid * WGM, gsz = (nM - fm) < WGM ? (nM - fm) : WGM;
;         u.pm = fm + ((wgid % nig) % gsz); u.pn = (wgid % nig) / gsz; return true;
; __device__ __forceinline__ void build_rstd_table(LAS unsigned char* lds, const float* ssp, const pg8::StaticOrder& S, int tid) {
;     ...
;     for (int k = 0; k < 6; ++k) { pg8::Unit u; ok[k] = S.next((tid >> 8) + 2 * k, u);
;         if (ok[k]) { const f32x4* q = (const f32x4*)(ssp + (size_t)(u.pm * 256 + (tid & 255)) * 16);
; #pragma unroll
;             for (int j = 0; j < 4; ++j) p[k][j] = q[j]; } }
.LBB0_421:
	s_or_b64 exec, exec, s[2:3]
	v_add_u32_e32 v18, 2, v80
	v_mov_b64_e32 v[16:17], s[96:97]
	v_mad_i64_i32 v[18:19], s[2:3], v18, s69, v[16:17]
	v_cmp_gt_i64_e64 s[8:9], s[26:27], v[18:19]
	s_and_saveexec_b64 s[2:3], s[8:9]
	s_cbranch_execz .LBB0_423
	v_ashrrev_i32_e32 v16, 31, v18
	v_lshrrev_b32_e32 v16, 29, v16
	v_add_u32_e32 v16, v18, v16
	v_ashrrev_i32_e32 v17, 3, v16
	v_and_b32_e32 v16, -8, v16
	v_sub_u32_e32 v16, v18, v16
	v_cmp_gt_i32_e64 s[10:11], 0, v16
	s_mov_b32 s4, 0x2e8ba2e9
	s_nop 0
	v_cndmask_b32_e64 v18, v200, v201, s[10:11]
	v_mul_lo_u32 v16, v16, v18
	v_add_u32_e32 v16, v16, v17
	v_mul_hi_i32 v17, v16, s4
	v_lshrrev_b32_e32 v18, 31, v17
	v_ashrrev_i32_e32 v17, 5, v17
	v_add_u32_e32 v17, v17, v18
	v_lshlrev_b32_e32 v18, 3, v17
	v_sub_u32_e32 v19, 0x80, v18
	v_min_i32_e32 v19, 8, v19
	v_sub_u32_e32 v20, 0, v19
	v_max_i32_e32 v19, v19, v20
	v_cvt_f32_u32_e32 v20, v19
	s_movk_i32 s4, 0xb0
	v_mul_lo_u32 v17, v17, s4
	v_sub_u32_e32 v16, v16, v17
	v_rcp_iflag_f32_e32 v20, v20
	v_sub_u32_e32 v21, 0, v16
	v_ashrrev_i32_e32 v17, 31, v16
	v_max_i32_e32 v16, v16, v21
	v_mul_f32_e32 v20, 0x4f7ffffe, v20
	v_cvt_u32_f32_e32 v20, v20
	v_sub_u32_e32 v21, 0, v19
	v_mul_lo_u32 v21, v21, v20
	v_mul_hi_u32 v21, v20, v21
	v_add_u32_e32 v20, v20, v21
	v_mul_hi_u32 v20, v16, v20
	v_mul_lo_u32 v20, v20, v19
	v_sub_u32_e32 v16, v16, v20
	v_sub_u32_e32 v20, v16, v19
	v_cmp_ge_u32_e64 s[10:11], v16, v19
	s_nop 1
	v_cndmask_b32_e64 v16, v16, v20, s[10:11]
	v_sub_u32_e32 v20, v16, v19
	v_cmp_ge_u32_e64 s[10:11], v16, v19
	s_nop 1
	v_cndmask_b32_e64 v16, v16, v20, s[10:11]
	v_xor_b32_e32 v16, v16, v17
	v_sub_u32_e32 v16, v16, v17
	v_add_u32_e32 v16, v18, v16
	v_lshl_or_b32 v16, v16, 8, v81
	v_ashrrev_i32_e32 v17, 31, v16
	v_lshlrev_b64 v[16:17], 6, v[16:17]
	v_lshl_add_u64 v[28:29], s[0:1], 0, v[16:17]
	global_load_dwordx4 v[16:19], v[28:29], off offset:48
	global_load_dwordx4 v[20:23], v[28:29], off offset:32
	global_load_dwordx4 v[24:27], v[28:29], off offset:16
	s_nop 0
	global_load_dwordx4 v[28:31], v[28:29], off
.LBB0_423:
	s_or_b64 exec, exec, s[2:3]
	v_add_u32_e32 v34, 4, v80
	v_mov_b64_e32 v[32:33], s[96:97]
	v_mad_i64_i32 v[34:35], s[2:3], v34, s69, v[32:33]
	v_cmp_gt_i64_e64 s[10:11], s[26:27], v[34:35]
	s_and_saveexec_b64 s[2:3], s[10:11]
	s_cbranch_execz .LBB0_425
	v_ashrrev_i32_e32 v32, 31, v34
	v_lshrrev_b32_e32 v32, 29, v32
	v_add_u32_e32 v32, v34, v32
	v_ashrrev_i32_e32 v33, 3, v32
	v_and_b32_e32 v32, -8, v32
	v_sub_u32_e32 v32, v34, v32
	v_cmp_gt_i32_e64 s[12:13], 0, v32
	s_mov_b32 s4, 0x2e8ba2e9
	s_nop 0
	v_cndmask_b32_e64 v34, v200, v201, s[12:13]
	v_mul_lo_u32 v32, v32, v34
	v_add_u32_e32 v32, v32, v33
	v_mul_hi_i32 v33, v32, s4
	v_lshrrev_b32_e32 v34, 31, v33
	v_ashrrev_i32_e32 v33, 5, v33
	v_add_u32_e32 v33, v33, v34
	v_lshlrev_b32_e32 v34, 3, v33
	v_sub_u32_e32 v35, 0x80, v34
	v_min_i32_e32 v35, 8, v35
	v_sub_u32_e32 v36, 0, v35
	v_max_i32_e32 v35, v35, v36
	v_cvt_f32_u32_e32 v36, v35
	s_movk_i32 s4, 0xb0
	v_mul_lo_u32 v33, v33, s4
	v_sub_u32_e32 v32, v32, v33
	v_rcp_iflag_f32_e32 v36, v36
	v_sub_u32_e32 v37, 0, v32
	v_ashrrev_i32_e32 v33, 31, v32
	v_max_i32_e32 v32, v32, v37
	v_mul_f32_e32 v36, 0x4f7ffffe, v36
	v_cvt_u32_f32_e32 v36, v36
	v_sub_u32_e32 v37, 0, v35
	v_mul_lo_u32 v37, v37, v36
	v_mul_hi_u32 v37, v36, v37
	v_add_u32_e32 v36, v36, v37
	v_mul_hi_u32 v36, v32, v36
	v_mul_lo_u32 v36, v36, v35
	v_sub_u32_e32 v32, v32, v36
	v_sub_u32_e32 v36, v32, v35
	v_cmp_ge_u32_e64 s[12:13], v32, v35
	s_nop 1
	v_cndmask_b32_e64 v32, v32, v36, s[12:13]
	v_sub_u32_e32 v36, v32, v35
	v_cmp_ge_u32_e64 s[12:13], v32, v35
	s_nop 1
	v_cndmask_b32_e64 v32, v32, v36, s[12:13]
	v_xor_b32_e32 v32, v32, v33
	v_sub_u32_e32 v32, v32, v33
	v_add_u32_e32 v32, v34, v32
	v_lshl_or_b32 v32, v32, 8, v81
	v_ashrrev_i32_e32 v33, 31, v32
	v_lshlrev_b64 v[32:33], 6, v[32:33]
	v_lshl_add_u64 v[44:45], s[0:1], 0, v[32:33]
	global_load_dwordx4 v[32:35], v[44:45], off offset:48
	global_load_dwordx4 v[36:39], v[44:45], off offset:32
	global_load_dwordx4 v[40:43], v[44:45], off offset:16
	s_nop 0
	global_load_dwordx4 v[44:47], v[44:45], off
.LBB0_425:
	s_or_b64 exec, exec, s[2:3]
	v_add_u32_e32 v50, 6, v80
	v_mov_b64_e32 v[48:49], s[96:97]
	v_mad_i64_i32 v[50:51], s[2:3], v50, s69, v[48:49]
	v_cmp_gt_i64_e64 s[12:13], s[26:27], v[50:51]
	s_and_saveexec_b64 s[2:3], s[12:13]
	s_cbranch_execz .LBB0_427
	v_ashrrev_i32_e32 v48, 31, v50
	v_lshrrev_b32_e32 v48, 29, v48
	v_add_u32_e32 v48, v50, v48
	v_ashrrev_i32_e32 v49, 3, v48
	v_and_b32_e32 v48, -8, v48
	v_sub_u32_e32 v48, v50, v48
	v_cmp_gt_i32_e64 s[14:15], 0, v48
	s_mov_b32 s4, 0x2e8ba2e9
	s_nop 0
	v_cndmask_b32_e64 v50, v200, v201, s[14:15]
	v_mul_lo_u32 v48, v48, v50
	v_add_u32_e32 v48, v48, v49
	v_mul_hi_i32 v49, v48, s4
	v_lshrrev_b32_e32 v50, 31, v49
	v_ashrrev_i32_e32 v49, 5, v49
	v_add_u32_e32 v49, v49, v50
	v_lshlrev_b32_e32 v50, 3, v49
	v_sub_u32_e32 v51, 0x80, v50
	v_min_i32_e32 v51, 8, v51
	v_sub_u32_e32 v52, 0, v51
	v_max_i32_e32 v51, v51, v52
	v_cvt_f32_u32_e32 v52, v51
	s_movk_i32 s4, 0xb0
	v_mul_lo_u32 v49, v49, s4
	v_sub_u32_e32 v48, v48, v49
	v_rcp_iflag_f32_e32 v52, v52
	v_sub_u32_e32 v53, 0, v48
	v_ashrrev_i32_e32 v49, 31, v48
	v_max_i32_e32 v48, v48, v53
	v_mul_f32_e32 v52, 0x4f7ffffe, v52
	v_cvt_u32_f32_e32 v52, v52
	v_sub_u32_e32 v53, 0, v51
	v_mul_lo_u32 v53, v53, v52
	v_mul_hi_u32 v53, v52, v53
	v_add_u32_e32 v52, v52, v53
	v_mul_hi_u32 v52, v48, v52
	v_mul_lo_u32 v52, v52, v51
	v_sub_u32_e32 v48, v48, v52
	v_sub_u32_e32 v52, v48, v51
	v_cmp_ge_u32_e64 s[14:15], v48, v51
	s_nop 1
	v_cndmask_b32_e64 v48, v48, v52, s[14:15]
	v_sub_u32_e32 v52, v48, v51
	v_cmp_ge_u32_e64 s[14:15], v48, v51
	s_nop 1
	v_cndmask_b32_e64 v48, v48, v52, s[14:15]
	v_xor_b32_e32 v48, v48, v49
	v_sub_u32_e32 v48, v48, v49
	v_add_u32_e32 v48, v50, v48
	v_lshl_or_b32 v48, v48, 8, v81
	v_ashrrev_i32_e32 v49, 31, v48
	v_lshlrev_b64 v[48:49], 6, v[48:49]
	v_lshl_add_u64 v[60:61], s[0:1], 0, v[48:49]
	global_load_dwordx4 v[48:51], v[60:61], off offset:48
	global_load_dwordx4 v[52:55], v[60:61], off offset:32
	global_load_dwordx4 v[56:59], v[60:61], off offset:16
	s_nop 0
	global_load_dwordx4 v[60:63], v[60:61], off
;     __host__ __device__ bool next(int i, Unit& u) const {
;         const long L = (long)i * G + c; if (L >= nwg) return false;
;         int wgid = (int)L; { const int q = nwg / NXCD, r = nwg % NXCD, xcd = wgid % NXCD, off = wgid / NXCD; wgid = (xcd < r ? xcd * (q + 1) : r * (q + 1) + (xcd - r) * q) + off; }
;         const int nig = WGM * nN, gid = wgid / nig, fm = gid * WGM, gsz = (nM - fm) < WGM ? (nM - fm) : WGM;
;         u.pm = fm + ((wgid % nig) % gsz); u.pn = (wgid % nig) / gsz; return true;
; __device__ __forceinline__ void build_rstd_table(LAS unsigned char* lds, const float* ssp, const pg8::StaticOrder& S, int tid) {
;     ...
;     for (int k = 0; k < 6; ++k) { pg8::Unit u; ok[k] = S.next((tid >> 8) + 2 * k, u);
;         if (ok[k]) { const f32x4* q = (const f32x4*)(ssp + (size_t)(u.pm * 256 + (tid & 255)) * 16);
; #pragma unroll
;             for (int j = 0; j < 4; ++j) p[k][j] = q[j]; } }
.LBB0_427:
	s_or_b64 exec, exec, s[2:3]
	v_add_u32_e32 v66, 8, v80
	v_mov_b64_e32 v[64:65], s[96:97]
	v_mad_i64_i32 v[66:67], s[2:3], v66, s69, v[64:65]
	v_cmp_gt_i64_e64 s[14:15], s[26:27], v[66:67]
	s_and_saveexec_b64 s[2:3], s[14:15]
	s_cbranch_execz .LBB0_429
	v_ashrrev_i32_e32 v64, 31, v66
	v_lshrrev_b32_e32 v64, 29, v64
	v_add_u32_e32 v64, v66, v64
	v_ashrrev_i32_e32 v65, 3, v64
	v_and_b32_e32 v64, -8, v64
	v_sub_u32_e32 v64, v66, v64
	v_cmp_gt_i32_e64 s[16:17], 0, v64
	s_mov_b32 s4, 0x2e8ba2e9
	s_nop 0
	v_cndmask_b32_e64 v66, v200, v201, s[16:17]
	v_mul_lo_u32 v64, v64, v66
	v_add_u32_e32 v64, v64, v65
	v_mul_hi_i32 v65, v64, s4
	v_lshrrev_b32_e32 v66, 31, v65
	v_ashrrev_i32_e32 v65, 5, v65
	v_add_u32_e32 v65, v65, v66
	v_lshlrev_b32_e32 v66, 3, v65
	v_sub_u32_e32 v67, 0x80, v66
	v_min_i32_e32 v67, 8, v67
	v_sub_u32_e32 v68, 0, v67
	v_max_i32_e32 v67, v67, v68
	v_cvt_f32_u32_e32 v68, v67
	s_movk_i32 s4, 0xb0
	v_mul_lo_u32 v65, v65, s4
	v_sub_u32_e32 v64, v64, v65
	v_rcp_iflag_f32_e32 v68, v68
	v_sub_u32_e32 v69, 0, v64
	v_ashrrev_i32_e32 v65, 31, v64
	v_max_i32_e32 v64, v64, v69
	v_mul_f32_e32 v68, 0x4f7ffffe, v68
	v_cvt_u32_f32_e32 v68, v68
	v_sub_u32_e32 v69, 0, v67
	v_mul_lo_u32 v69, v69, v68
	v_mul_hi_u32 v69, v68, v69
	v_add_u32_e32 v68, v68, v69
	v_mul_hi_u32 v68, v64, v68
	v_mul_lo_u32 v68, v68, v67
	v_sub_u32_e32 v64, v64, v68
	v_sub_u32_e32 v68, v64, v67
	v_cmp_ge_u32_e64 s[16:17], v64, v67
	s_nop 1
	v_cndmask_b32_e64 v64, v64, v68, s[16:17]
	v_sub_u32_e32 v68, v64, v67
	v_cmp_ge_u32_e64 s[16:17], v64, v67
	s_nop 1
	v_cndmask_b32_e64 v64, v64, v68, s[16:17]
	v_xor_b32_e32 v64, v64, v65
	v_sub_u32_e32 v64, v64, v65
	v_add_u32_e32 v64, v66, v64
	v_lshl_or_b32 v64, v64, 8, v81
	v_ashrrev_i32_e32 v65, 31, v64
	v_lshlrev_b64 v[64:65], 6, v[64:65]
	v_lshl_add_u64 v[76:77], s[0:1], 0, v[64:65]
	global_load_dwordx4 v[64:67], v[76:77], off offset:16
	global_load_dwordx4 v[72:75], v[76:77], off
	global_load_dwordx4 v[68:71], v[76:77], off offset:32
	s_nop 0
	global_load_dwordx4 v[76:79], v[76:77], off offset:48
.LBB0_429:
	s_or_b64 exec, exec, s[2:3]
	v_add_u32_e32 v80, 10, v80
	v_mov_b64_e32 v[82:83], s[96:97]
	v_mad_i64_i32 v[82:83], s[2:3], v80, s69, v[82:83]
	v_cmp_gt_i64_e64 s[16:17], s[26:27], v[82:83]
	s_and_saveexec_b64 s[2:3], s[16:17]
	s_cbranch_execz .LBB0_452
	v_ashrrev_i32_e32 v80, 31, v82
	v_lshrrev_b32_e32 v80, 29, v80
	v_add_u32_e32 v80, v82, v80
	v_ashrrev_i32_e32 v83, 3, v80
	v_and_b32_e32 v80, -8, v80
	v_sub_u32_e32 v80, v82, v80
	v_cmp_gt_i32_e64 s[18:19], 0, v80
	s_mov_b32 s4, 0x2e8ba2e9
	s_nop 0
	v_cndmask_b32_e64 v82, v200, v201, s[18:19]
	v_mul_lo_u32 v80, v80, v82
	v_add_u32_e32 v80, v80, v83
	v_mul_hi_i32 v82, v80, s4
	v_lshrrev_b32_e32 v83, 31, v82
	v_ashrrev_i32_e32 v82, 5, v82
	v_add_u32_e32 v82, v82, v83
	v_lshlrev_b32_e32 v83, 3, v82
	v_sub_u32_e32 v84, 0x80, v83
	v_min_i32_e32 v84, 8, v84
	v_sub_u32_e32 v85, 0, v84
	v_max_i32_e32 v84, v84, v85
	v_cvt_f32_u32_e32 v85, v84
	s_movk_i32 s4, 0xb0
	v_mul_lo_u32 v82, v82, s4
	v_sub_u32_e32 v80, v80, v82
	v_rcp_iflag_f32_e32 v85, v85
	v_sub_u32_e32 v86, 0, v80
	v_ashrrev_i32_e32 v82, 31, v80
	v_max_i32_e32 v80, v80, v86
	v_mul_f32_e32 v85, 0x4f7ffffe, v85
	v_cvt_u32_f32_e32 v85, v85
	v_sub_u32_e32 v86, 0, v84
	v_mul_lo_u32 v86, v86, v85
	v_mul_hi_u32 v86, v85, v86
	v_add_u32_e32 v85, v85, v86
	v_mul_hi_u32 v85, v80, v85
	v_mul_lo_u32 v85, v85, v84
	v_sub_u32_e32 v80, v80, v85
	v_sub_u32_e32 v85, v80, v84
	v_cmp_ge_u32_e64 s[18:19], v80, v84
	s_nop 1
	v_cndmask_b32_e64 v80, v80, v85, s[18:19]
	v_sub_u32_e32 v85, v80, v84
	v_cmp_ge_u32_e64 s[18:19], v80, v84
	s_nop 1
	v_cndmask_b32_e64 v80, v80, v85, s[18:19]
	v_xor_b32_e32 v80, v80, v82
	v_sub_u32_e32 v80, v80, v82
	v_add_u32_e32 v80, v83, v80
	v_lshl_or_b32 v80, v80, 8, v81
	v_ashrrev_i32_e32 v81, 31, v80
	v_lshlrev_b64 v[80:81], 6, v[80:81]
	v_lshl_add_u64 v[92:93], s[0:1], 0, v[80:81]
	global_load_dwordx4 v[80:83], v[92:93], off
	global_load_dwordx4 v[84:87], v[92:93], off offset:16
	global_load_dwordx4 v[88:91], v[92:93], off offset:32
	s_nop 0
	global_load_dwordx4 v[92:95], v[92:93], off offset:48
	s_or_b64 exec, exec, s[2:3]
	s_and_saveexec_b64 s[0:1], vcc
	s_cbranch_execnz .LBB0_453

;     __host__ __device__ bool next(int i, Unit& u) const {
;         const long L = (long)i * G + c; if (L >= nwg) return false;
;         int wgid = (int)L; { const int q = nwg / NXCD, r = nwg % NXCD, xcd = wgid % NXCD, off = wgid / NXCD; wgid = (xcd < r ? xcd * (q + 1) : r * (q + 1) + (xcd - r) * q) + off; }
;         const int nig = WGM * nN, gid = wgid / nig, fm = gid * WGM, gsz = (nM - fm) < WGM ? (nM - fm) : WGM;
;         u.pm = fm + ((wgid % nig) % gsz); u.pn = (wgid % nig) / gsz; return true;
; __device__ __forceinline__ void build_rstd_table(LAS unsigned char* lds, const float* ssp, const pg8::StaticOrder& S, int tid) {
;     ...
;     for (int k = 0; k < 6; ++k) { pg8::Unit u; ok[k] = S.next((tid >> 8) + 2 * k, u);
;         if (ok[k]) { const f32x4* q = (const f32x4*)(ssp + (size_t)(u.pm * 256 + (tid & 255)) * 16);
; #pragma unroll
;             for (int j = 0; j < 4; ++j) p[k][j] = q[j]; } }
.LBB0_675:
	s_or_b64 exec, exec, s[2:3]
	v_add_u32_e32 v18, 2, v80
	v_mov_b64_e32 v[16:17], s[96:97]
	v_mad_i64_i32 v[16:17], s[2:3], v18, s69, v[16:17]
	s_mov_b64 s[2:3], 0x400
	s_nop 0
	v_cmp_gt_i64_e64 s[8:9], s[2:3], v[16:17]
	s_and_saveexec_b64 s[2:3], s[8:9]
	s_cbranch_execz .LBB0_681
	v_ashrrev_i32_e32 v17, 31, v16
	v_lshrrev_b32_e32 v17, 29, v17
	v_add_u32_e32 v17, v16, v17
	v_and_b32_e32 v18, -8, v17
	v_sub_u32_e32 v18, v16, v18
	v_cmp_lt_i32_e64 s[10:11], -1, v18
	s_and_saveexec_b64 s[4:5], s[10:11]
	s_xor_b64 s[4:5], exec, s[4:5]
	v_lshlrev_b32_e32 v16, 7, v18
	s_andn2_saveexec_b64 s[4:5], s[4:5]
	v_lshl_add_u32 v16, v18, 7, v18
	s_or_b64 exec, exec, s[4:5]
	v_ashrrev_i32_e32 v17, 3, v17
	v_add_u32_e32 v16, v16, v17
	v_ashrrev_i32_e32 v17, 31, v16
	v_lshrrev_b32_e32 v17, 26, v17
	v_add_u32_e32 v17, v16, v17
	v_ashrrev_i32_e32 v18, 6, v17
	v_lshlrev_b32_e32 v18, 3, v18
	v_sub_u32_e32 v19, 0x80, v18
	v_min_i32_e32 v19, 8, v19
	v_sub_u32_e32 v20, 0, v19
	v_max_i32_e32 v19, v19, v20
	v_cvt_f32_u32_e32 v20, v19
	v_and_b32_e32 v17, 0xffffffc0, v17
	v_sub_u32_e32 v16, v16, v17
	v_sub_u32_e32 v21, 0, v16
	v_rcp_iflag_f32_e32 v20, v20
	v_ashrrev_i32_e32 v17, 31, v16
	v_max_i32_e32 v16, v16, v21
	v_sub_u32_e32 v21, 0, v19
	v_mul_f32_e32 v20, 0x4f7ffffe, v20
	v_cvt_u32_f32_e32 v20, v20
	v_mul_lo_u32 v21, v21, v20
	v_mul_hi_u32 v21, v20, v21
	v_add_u32_e32 v20, v20, v21
	v_mul_hi_u32 v20, v16, v20
	v_mul_lo_u32 v20, v20, v19
	v_sub_u32_e32 v16, v16, v20
	v_sub_u32_e32 v20, v16, v19
	v_cmp_ge_u32_e64 s[10:11], v16, v19
	s_nop 1
	v_cndmask_b32_e64 v16, v16, v20, s[10:11]
	v_sub_u32_e32 v20, v16, v19
	v_cmp_ge_u32_e64 s[10:11], v16, v19
	s_nop 1
	v_cndmask_b32_e64 v16, v16, v20, s[10:11]
	v_xor_b32_e32 v16, v16, v17
	v_sub_u32_e32 v16, v16, v17
	v_add_u32_e32 v16, v18, v16
	v_lshl_or_b32 v16, v16, 8, v82
	v_ashrrev_i32_e32 v17, 31, v16
	v_lshlrev_b64 v[16:17], 6, v[16:17]
	v_lshl_add_u64 v[28:29], s[0:1], 0, v[16:17]
	global_load_dwordx4 v[16:19], v[28:29], off offset:48
	global_load_dwordx4 v[20:23], v[28:29], off offset:32
	global_load_dwordx4 v[24:27], v[28:29], off offset:16
	s_nop 0
	global_load_dwordx4 v[28:31], v[28:29], off
.LBB0_681:
	s_or_b64 exec, exec, s[2:3]
	v_add_u32_e32 v34, 4, v80
	v_mov_b64_e32 v[32:33], s[96:97]
	v_mad_i64_i32 v[32:33], s[2:3], v34, s69, v[32:33]
	s_mov_b64 s[2:3], 0x400
	s_nop 0
	v_cmp_gt_i64_e64 s[10:11], s[2:3], v[32:33]
	s_and_saveexec_b64 s[2:3], s[10:11]
	s_cbranch_execz .LBB0_687
	v_ashrrev_i32_e32 v33, 31, v32
	v_lshrrev_b32_e32 v33, 29, v33
	v_add_u32_e32 v33, v32, v33
	v_and_b32_e32 v34, -8, v33
	v_sub_u32_e32 v34, v32, v34
	v_cmp_lt_i32_e64 s[12:13], -1, v34
	s_and_saveexec_b64 s[4:5], s[12:13]
	s_xor_b64 s[4:5], exec, s[4:5]
	v_lshlrev_b32_e32 v32, 7, v34
	s_andn2_saveexec_b64 s[4:5], s[4:5]
	v_lshl_add_u32 v32, v34, 7, v34
	s_or_b64 exec, exec, s[4:5]
	v_ashrrev_i32_e32 v33, 3, v33
	v_add_u32_e32 v32, v32, v33
	v_ashrrev_i32_e32 v33, 31, v32
	v_lshrrev_b32_e32 v33, 26, v33
	v_add_u32_e32 v33, v32, v33
	v_ashrrev_i32_e32 v34, 6, v33
	v_lshlrev_b32_e32 v34, 3, v34
	v_sub_u32_e32 v35, 0x80, v34
	v_min_i32_e32 v35, 8, v35
	v_sub_u32_e32 v36, 0, v35
	v_max_i32_e32 v35, v35, v36
	v_cvt_f32_u32_e32 v36, v35
	v_and_b32_e32 v33, 0xffffffc0, v33
	v_sub_u32_e32 v32, v32, v33
	v_sub_u32_e32 v37, 0, v32
	v_rcp_iflag_f32_e32 v36, v36
	v_ashrrev_i32_e32 v33, 31, v32
	v_max_i32_e32 v32, v32, v37
	v_sub_u32_e32 v37, 0, v35
	v_mul_f32_e32 v36, 0x4f7ffffe, v36
	v_cvt_u32_f32_e32 v36, v36
	v_mul_lo_u32 v37, v37, v36
	v_mul_hi_u32 v37, v36, v37
	v_add_u32_e32 v36, v36, v37
	v_mul_hi_u32 v36, v32, v36
	v_mul_lo_u32 v36, v36, v35
	v_sub_u32_e32 v32, v32, v36
	v_sub_u32_e32 v36, v32, v35
	v_cmp_ge_u32_e64 s[12:13], v32, v35
	s_nop 1
	v_cndmask_b32_e64 v32, v32, v36, s[12:13]
	v_sub_u32_e32 v36, v32, v35
	v_cmp_ge_u32_e64 s[12:13], v32, v35
	s_nop 1
	v_cndmask_b32_e64 v32, v32, v36, s[12:13]
	v_xor_b32_e32 v32, v32, v33
	v_sub_u32_e32 v32, v32, v33
	v_add_u32_e32 v32, v34, v32
	v_lshl_or_b32 v32, v32, 8, v82
	v_ashrrev_i32_e32 v33, 31, v32
	v_lshlrev_b64 v[32:33], 6, v[32:33]
	v_lshl_add_u64 v[44:45], s[0:1], 0, v[32:33]
	global_load_dwordx4 v[32:35], v[44:45], off offset:48
	global_load_dwordx4 v[36:39], v[44:45], off offset:32
	global_load_dwordx4 v[40:43], v[44:45], off offset:16
	s_nop 0
	global_load_dwordx4 v[44:47], v[44:45], off
.LBB0_687:
	s_or_b64 exec, exec, s[2:3]
	v_add_u32_e32 v50, 6, v80
	v_mov_b64_e32 v[48:49], s[96:97]
	v_mad_i64_i32 v[48:49], s[2:3], v50, s69, v[48:49]
	s_mov_b64 s[2:3], 0x400
	s_nop 0
	v_cmp_gt_i64_e64 s[12:13], s[2:3], v[48:49]
	s_and_saveexec_b64 s[2:3], s[12:13]
	s_cbranch_execz .LBB0_693
	v_ashrrev_i32_e32 v49, 31, v48
	v_lshrrev_b32_e32 v49, 29, v49
	v_add_u32_e32 v49, v48, v49
	v_and_b32_e32 v50, -8, v49
	v_sub_u32_e32 v50, v48, v50
	v_cmp_lt_i32_e64 s[14:15], -1, v50
	s_and_saveexec_b64 s[4:5], s[14:15]
	s_xor_b64 s[4:5], exec, s[4:5]
	v_lshlrev_b32_e32 v48, 7, v50
	s_andn2_saveexec_b64 s[4:5], s[4:5]
	v_lshl_add_u32 v48, v50, 7, v50
	s_or_b64 exec, exec, s[4:5]
	v_ashrrev_i32_e32 v49, 3, v49
	v_add_u32_e32 v48, v48, v49
	v_ashrrev_i32_e32 v49, 31, v48
	v_lshrrev_b32_e32 v49, 26, v49
	v_add_u32_e32 v49, v48, v49
	v_ashrrev_i32_e32 v50, 6, v49
	v_lshlrev_b32_e32 v50, 3, v50
	v_sub_u32_e32 v51, 0x80, v50
	v_min_i32_e32 v51, 8, v51
	v_sub_u32_e32 v52, 0, v51
	v_max_i32_e32 v51, v51, v52
	v_cvt_f32_u32_e32 v52, v51
	v_and_b32_e32 v49, 0xffffffc0, v49
	v_sub_u32_e32 v48, v48, v49
	v_sub_u32_e32 v53, 0, v48
	v_rcp_iflag_f32_e32 v52, v52
	v_ashrrev_i32_e32 v49, 31, v48
	v_max_i32_e32 v48, v48, v53
	v_sub_u32_e32 v53, 0, v51
	v_mul_f32_e32 v52, 0x4f7ffffe, v52
	v_cvt_u32_f32_e32 v52, v52
	v_mul_lo_u32 v53, v53, v52
	v_mul_hi_u32 v53, v52, v53
	v_add_u32_e32 v52, v52, v53
	v_mul_hi_u32 v52, v48, v52
	v_mul_lo_u32 v52, v52, v51
	v_sub_u32_e32 v48, v48, v52
	v_sub_u32_e32 v52, v48, v51
	v_cmp_ge_u32_e64 s[14:15], v48, v51
	s_nop 1
	v_cndmask_b32_e64 v48, v48, v52, s[14:15]
	v_sub_u32_e32 v52, v48, v51
	v_cmp_ge_u32_e64 s[14:15], v48, v51
	s_nop 1
	v_cndmask_b32_e64 v48, v48, v52, s[14:15]
	v_xor_b32_e32 v48, v48, v49
	v_sub_u32_e32 v48, v48, v49
	v_add_u32_e32 v48, v50, v48
	v_lshl_or_b32 v48, v48, 8, v82
	v_ashrrev_i32_e32 v49, 31, v48
	v_lshlrev_b64 v[48:49], 6, v[48:49]
	v_lshl_add_u64 v[60:61], s[0:1], 0, v[48:49]
	global_load_dwordx4 v[48:51], v[60:61], off offset:48
	global_load_dwordx4 v[52:55], v[60:61], off offset:32
	global_load_dwordx4 v[56:59], v[60:61], off offset:16
	s_nop 0
	global_load_dwordx4 v[60:63], v[60:61], off
;     __host__ __device__ bool next(int i, Unit& u) const {
;         const long L = (long)i * G + c; if (L >= nwg) return false;
;         int wgid = (int)L; { const int q = nwg / NXCD, r = nwg % NXCD, xcd = wgid % NXCD, off = wgid / NXCD; wgid = (xcd < r ? xcd * (q + 1) : r * (q + 1) + (xcd - r) * q) + off; }
;         const int nig = WGM * nN, gid = wgid / nig, fm = gid * WGM, gsz = (nM - fm) < WGM ? (nM - fm) : WGM;
;         u.pm = fm + ((wgid % nig) % gsz); u.pn = (wgid % nig) / gsz; return true;
; __device__ __forceinline__ void build_rstd_table(LAS unsigned char* lds, const float* ssp, const pg8::StaticOrder& S, int tid) {
;     ...
;     for (int k = 0; k < 6; ++k) { pg8::Unit u; ok[k] = S.next((tid >> 8) + 2 * k, u);
;         if (ok[k]) { const f32x4* q = (const f32x4*)(ssp + (size_t)(u.pm * 256 + (tid & 255)) * 16);
; #pragma unroll
;             for (int j = 0; j < 4; ++j) p[k][j] = q[j]; } }
.LBB0_693:
	s_or_b64 exec, exec, s[2:3]
	v_add_u32_e32 v66, 8, v80
	v_mov_b64_e32 v[64:65], s[96:97]
	v_mad_i64_i32 v[64:65], s[2:3], v66, s69, v[64:65]
	s_mov_b64 s[2:3], 0x400
	s_nop 0
	v_cmp_gt_i64_e64 s[14:15], s[2:3], v[64:65]
	s_and_saveexec_b64 s[2:3], s[14:15]
	s_cbranch_execz .LBB0_699
	v_ashrrev_i32_e32 v65, 31, v64
	v_lshrrev_b32_e32 v65, 29, v65
	v_add_u32_e32 v65, v64, v65
	v_and_b32_e32 v66, -8, v65
	v_sub_u32_e32 v66, v64, v66
	v_cmp_lt_i32_e64 s[16:17], -1, v66
	s_and_saveexec_b64 s[4:5], s[16:17]
	s_xor_b64 s[4:5], exec, s[4:5]
	v_lshlrev_b32_e32 v64, 7, v66
	s_andn2_saveexec_b64 s[4:5], s[4:5]
	v_lshl_add_u32 v64, v66, 7, v66
	s_or_b64 exec, exec, s[4:5]
	v_ashrrev_i32_e32 v65, 3, v65
	v_add_u32_e32 v64, v64, v65
	v_ashrrev_i32_e32 v65, 31, v64
	v_lshrrev_b32_e32 v65, 26, v65
	v_add_u32_e32 v65, v64, v65
	v_ashrrev_i32_e32 v66, 6, v65
	v_lshlrev_b32_e32 v66, 3, v66
	v_sub_u32_e32 v67, 0x80, v66
	v_min_i32_e32 v67, 8, v67
	v_sub_u32_e32 v68, 0, v67
	v_max_i32_e32 v67, v67, v68
	v_cvt_f32_u32_e32 v68, v67
	v_and_b32_e32 v65, 0xffffffc0, v65
	v_sub_u32_e32 v64, v64, v65
	v_sub_u32_e32 v69, 0, v64
	v_rcp_iflag_f32_e32 v68, v68
	v_ashrrev_i32_e32 v65, 31, v64
	v_max_i32_e32 v64, v64, v69
	v_sub_u32_e32 v69, 0, v67
	v_mul_f32_e32 v68, 0x4f7ffffe, v68
	v_cvt_u32_f32_e32 v68, v68
	v_mul_lo_u32 v69, v69, v68
	v_mul_hi_u32 v69, v68, v69
	v_add_u32_e32 v68, v68, v69
	v_mul_hi_u32 v68, v64, v68
	v_mul_lo_u32 v68, v68, v67
	v_sub_u32_e32 v64, v64, v68
	v_sub_u32_e32 v68, v64, v67
	v_cmp_ge_u32_e64 s[16:17], v64, v67
	s_nop 1
	v_cndmask_b32_e64 v64, v64, v68, s[16:17]
	v_sub_u32_e32 v68, v64, v67
	v_cmp_ge_u32_e64 s[16:17], v64, v67
	s_nop 1
	v_cndmask_b32_e64 v64, v64, v68, s[16:17]
	v_xor_b32_e32 v64, v64, v65
	v_sub_u32_e32 v64, v64, v65
	v_add_u32_e32 v64, v66, v64
	v_lshl_or_b32 v64, v64, 8, v82
	v_ashrrev_i32_e32 v65, 31, v64
	v_lshlrev_b64 v[64:65], 6, v[64:65]
	v_lshl_add_u64 v[64:65], s[0:1], 0, v[64:65]
	global_load_dwordx4 v[72:75], v[64:65], off offset:16
	global_load_dwordx4 v[76:79], v[64:65], off
	global_load_dwordx4 v[68:71], v[64:65], off offset:32
	s_nop 0
	global_load_dwordx4 v[64:67], v[64:65], off offset:48
.LBB0_699:
	s_or_b64 exec, exec, s[2:3]
	v_add_u32_e32 v83, 10, v80
	v_mov_b64_e32 v[80:81], s[96:97]
	v_mad_i64_i32 v[80:81], s[2:3], v83, s69, v[80:81]
	s_mov_b64 s[2:3], 0x400
	s_nop 0
	v_cmp_gt_i64_e64 s[16:17], s[2:3], v[80:81]
	s_and_saveexec_b64 s[2:3], s[16:17]
	s_cbranch_execz .LBB0_802
	v_ashrrev_i32_e32 v81, 31, v80
	v_lshrrev_b32_e32 v81, 29, v81
	v_add_u32_e32 v81, v80, v81
	v_and_b32_e32 v83, -8, v81
	v_sub_u32_e32 v83, v80, v83
	v_cmp_lt_i32_e64 s[18:19], -1, v83
	s_and_saveexec_b64 s[4:5], s[18:19]
	s_xor_b64 s[4:5], exec, s[4:5]
	v_lshlrev_b32_e32 v80, 7, v83
	s_andn2_saveexec_b64 s[4:5], s[4:5]
	v_lshl_add_u32 v80, v83, 7, v83
	s_or_b64 exec, exec, s[4:5]
	v_ashrrev_i32_e32 v81, 3, v81
	v_add_u32_e32 v80, v80, v81
	v_ashrrev_i32_e32 v81, 31, v80
	v_lshrrev_b32_e32 v81, 26, v81
	v_add_u32_e32 v81, v80, v81
	v_ashrrev_i32_e32 v83, 6, v81
	v_lshlrev_b32_e32 v83, 3, v83
	v_sub_u32_e32 v84, 0x80, v83
	v_min_i32_e32 v84, 8, v84
	v_sub_u32_e32 v85, 0, v84
	v_max_i32_e32 v84, v84, v85
	v_cvt_f32_u32_e32 v85, v84
	v_and_b32_e32 v81, 0xffffffc0, v81
	v_sub_u32_e32 v80, v80, v81
	v_sub_u32_e32 v86, 0, v80
	v_rcp_iflag_f32_e32 v85, v85
	v_ashrrev_i32_e32 v81, 31, v80
	v_max_i32_e32 v80, v80, v86
	v_sub_u32_e32 v86, 0, v84
	v_mul_f32_e32 v85, 0x4f7ffffe, v85
	v_cvt_u32_f32_e32 v85, v85
	v_mul_lo_u32 v86, v86, v85
	v_mul_hi_u32 v86, v85, v86
	v_add_u32_e32 v85, v85, v86
	v_mul_hi_u32 v85, v80, v85
	v_mul_lo_u32 v85, v85, v84
	v_sub_u32_e32 v80, v80, v85
	v_sub_u32_e32 v85, v80, v84
	v_cmp_ge_u32_e64 s[18:19], v80, v84
	s_nop 1
	v_cndmask_b32_e64 v80, v80, v85, s[18:19]
	v_sub_u32_e32 v85, v80, v84
	v_cmp_ge_u32_e64 s[18:19], v80, v84
	s_nop 1
	v_cndmask_b32_e64 v80, v80, v85, s[18:19]
	v_xor_b32_e32 v80, v80, v81
	v_sub_u32_e32 v80, v80, v81
	v_add_u32_e32 v80, v83, v80
	v_lshl_or_b32 v80, v80, 8, v82
	v_ashrrev_i32_e32 v81, 31, v80
	v_lshlrev_b64 v[80:81], 6, v[80:81]
	v_lshl_add_u64 v[80:81], s[0:1], 0, v[80:81]
	global_load_dwordx4 v[92:95], v[80:81], off
	global_load_dwordx4 v[88:91], v[80:81], off offset:16
	global_load_dwordx4 v[84:87], v[80:81], off offset:32
	s_nop 0
	global_load_dwordx4 v[80:83], v[80:81], off offset:48
	s_or_b64 exec, exec, s[2:3]
	s_and_saveexec_b64 s[0:1], vcc
	s_cbranch_execnz .LBB0_803

;     __host__ __device__ bool next(int i, Unit& u) const {
;         const long L = (long)i * G + c; if (L >= nwg) return false;
;         int wgid = (int)L; { const int q = nwg / NXCD, r = nwg % NXCD, xcd = wgid % NXCD, off = wgid / NXCD; wgid = (xcd < r ? xcd * (q + 1) : r * (q + 1) + (xcd - r) * q) + off; }
;         const int nig = WGM * nN, gid = wgid / nig, fm = gid * WGM, gsz = (nM - fm) < WGM ? (nM - fm) : WGM;
;         u.pm = fm + ((wgid % nig) % gsz); u.pn = (wgid % nig) / gsz; return true;
; __device__ __forceinline__ void build_rstd_table(LAS unsigned char* lds, const float* ssp, const pg8::StaticOrder& S, int tid) {
;     ...
;     for (int k = 0; k < 6; ++k) { pg8::Unit u; ok[k] = S.next((tid >> 8) + 2 * k, u);
;         if (ok[k]) { const f32x4* q = (const f32x4*)(ssp + (size_t)(u.pm * 256 + (tid & 255)) * 16);
; #pragma unroll
;             for (int j = 0; j < 4; ++j) p[k][j] = q[j]; } }
.LBB0_720:
	s_or_b64 exec, exec, s[2:3]
	v_add_u32_e32 v18, 2, v80
	v_mov_b64_e32 v[16:17], s[96:97]
	v_mad_i64_i32 v[18:19], s[2:3], v18, s69, v[16:17]
	s_mov_b64 s[2:3], 0x300
	s_nop 0
	v_cmp_gt_i64_e64 s[8:9], s[2:3], v[18:19]
	s_and_saveexec_b64 s[2:3], s[8:9]
	s_cbranch_execz .LBB0_722
	v_ashrrev_i32_e32 v16, 31, v18
	v_lshrrev_b32_e32 v16, 29, v16
	v_add_u32_e32 v16, v18, v16
	v_ashrrev_i32_e32 v17, 3, v16
	v_and_b32_e32 v16, -8, v16
	v_sub_u32_e32 v16, v18, v16
	v_cmp_gt_i32_e64 s[10:11], 0, v16
	v_mov_b32_e32 v18, 0x61
	s_mov_b32 s4, 0x2aaaaaab
	v_cndmask_b32_e64 v18, v198, v18, s[10:11]
	v_mul_lo_u32 v16, v16, v18
	v_add_u32_e32 v16, v16, v17
	v_mul_hi_i32 v17, v16, s4
	v_lshrrev_b32_e32 v18, 31, v17
	v_ashrrev_i32_e32 v17, 3, v17
	v_add_u32_e32 v17, v17, v18
	v_lshlrev_b32_e32 v18, 3, v17
	v_sub_u32_e32 v19, 0x80, v18
	v_min_i32_e32 v19, 8, v19
	v_sub_u32_e32 v20, 0, v19
	v_max_i32_e32 v19, v19, v20
	v_cvt_f32_u32_e32 v20, v19
	v_mul_lo_u32 v17, v17, 48
	v_sub_u32_e32 v16, v16, v17
	v_sub_u32_e32 v21, 0, v16
	v_rcp_iflag_f32_e32 v20, v20
	v_ashrrev_i32_e32 v17, 31, v16
	v_max_i32_e32 v16, v16, v21
	v_sub_u32_e32 v21, 0, v19
	v_mul_f32_e32 v20, 0x4f7ffffe, v20
	v_cvt_u32_f32_e32 v20, v20
	v_mul_lo_u32 v21, v21, v20
	v_mul_hi_u32 v21, v20, v21
	v_add_u32_e32 v20, v20, v21
	v_mul_hi_u32 v20, v16, v20
	v_mul_lo_u32 v20, v20, v19
	v_sub_u32_e32 v16, v16, v20
	v_sub_u32_e32 v20, v16, v19
	v_cmp_ge_u32_e64 s[10:11], v16, v19
	s_nop 1
	v_cndmask_b32_e64 v16, v16, v20, s[10:11]
	v_sub_u32_e32 v20, v16, v19
	v_cmp_ge_u32_e64 s[10:11], v16, v19
	s_nop 1
	v_cndmask_b32_e64 v16, v16, v20, s[10:11]
	v_xor_b32_e32 v16, v16, v17
	v_sub_u32_e32 v16, v16, v17
	v_add_u32_e32 v16, v18, v16
	v_lshl_or_b32 v16, v16, 8, v81
	v_ashrrev_i32_e32 v17, 31, v16
	v_lshlrev_b64 v[16:17], 6, v[16:17]
	v_lshl_add_u64 v[28:29], s[0:1], 0, v[16:17]
	global_load_dwordx4 v[16:19], v[28:29], off offset:48
	global_load_dwordx4 v[20:23], v[28:29], off offset:32
	global_load_dwordx4 v[24:27], v[28:29], off offset:16
	s_nop 0
	global_load_dwordx4 v[28:31], v[28:29], off
.LBB0_722:
	s_or_b64 exec, exec, s[2:3]
	v_add_u32_e32 v34, 4, v80
	v_mov_b64_e32 v[32:33], s[96:97]
	v_mad_i64_i32 v[34:35], s[2:3], v34, s69, v[32:33]
	s_mov_b64 s[2:3], 0x300
	s_nop 0
	v_cmp_gt_i64_e64 s[10:11], s[2:3], v[34:35]
	s_and_saveexec_b64 s[2:3], s[10:11]
	s_cbranch_execz .LBB0_724
	v_ashrrev_i32_e32 v32, 31, v34
	v_lshrrev_b32_e32 v32, 29, v32
	v_add_u32_e32 v32, v34, v32
	v_ashrrev_i32_e32 v33, 3, v32
	v_and_b32_e32 v32, -8, v32
	v_sub_u32_e32 v32, v34, v32
	v_cmp_gt_i32_e64 s[12:13], 0, v32
	v_mov_b32_e32 v34, 0x61
	s_mov_b32 s4, 0x2aaaaaab
	v_cndmask_b32_e64 v34, v198, v34, s[12:13]
	v_mul_lo_u32 v32, v32, v34
	v_add_u32_e32 v32, v32, v33
	v_mul_hi_i32 v33, v32, s4
	v_lshrrev_b32_e32 v34, 31, v33
	v_ashrrev_i32_e32 v33, 3, v33
	v_add_u32_e32 v33, v33, v34
	v_lshlrev_b32_e32 v34, 3, v33
	v_sub_u32_e32 v35, 0x80, v34
	v_min_i32_e32 v35, 8, v35
	v_sub_u32_e32 v36, 0, v35
	v_max_i32_e32 v35, v35, v36
	v_cvt_f32_u32_e32 v36, v35
	v_mul_lo_u32 v33, v33, 48
	v_sub_u32_e32 v32, v32, v33
	v_sub_u32_e32 v37, 0, v32
	v_rcp_iflag_f32_e32 v36, v36
	v_ashrrev_i32_e32 v33, 31, v32
	v_max_i32_e32 v32, v32, v37
	v_sub_u32_e32 v37, 0, v35
	v_mul_f32_e32 v36, 0x4f7ffffe, v36
	v_cvt_u32_f32_e32 v36, v36
	v_mul_lo_u32 v37, v37, v36
	v_mul_hi_u32 v37, v36, v37
	v_add_u32_e32 v36, v36, v37
	v_mul_hi_u32 v36, v32, v36
	v_mul_lo_u32 v36, v36, v35
	v_sub_u32_e32 v32, v32, v36
	v_sub_u32_e32 v36, v32, v35
	v_cmp_ge_u32_e64 s[12:13], v32, v35
	s_nop 1
	v_cndmask_b32_e64 v32, v32, v36, s[12:13]
	v_sub_u32_e32 v36, v32, v35
	v_cmp_ge_u32_e64 s[12:13], v32, v35
	s_nop 1
	v_cndmask_b32_e64 v32, v32, v36, s[12:13]
	v_xor_b32_e32 v32, v32, v33
	v_sub_u32_e32 v32, v32, v33
	v_add_u32_e32 v32, v34, v32
	v_lshl_or_b32 v32, v32, 8, v81
	v_ashrrev_i32_e32 v33, 31, v32
	v_lshlrev_b64 v[32:33], 6, v[32:33]
	v_lshl_add_u64 v[44:45], s[0:1], 0, v[32:33]
	global_load_dwordx4 v[32:35], v[44:45], off offset:48
	global_load_dwordx4 v[36:39], v[44:45], off offset:32
	global_load_dwordx4 v[40:43], v[44:45], off offset:16
	s_nop 0
	global_load_dwordx4 v[44:47], v[44:45], off
.LBB0_724:
	s_or_b64 exec, exec, s[2:3]
	v_add_u32_e32 v50, 6, v80
	v_mov_b64_e32 v[48:49], s[96:97]
	v_mad_i64_i32 v[50:51], s[2:3], v50, s69, v[48:49]
	s_mov_b64 s[2:3], 0x300
	s_nop 0
	v_cmp_gt_i64_e64 s[12:13], s[2:3], v[50:51]
	s_and_saveexec_b64 s[2:3], s[12:13]
	s_cbranch_execz .LBB0_726
	v_ashrrev_i32_e32 v48, 31, v50
	v_lshrrev_b32_e32 v48, 29, v48
	v_add_u32_e32 v48, v50, v48
	v_ashrrev_i32_e32 v49, 3, v48
	v_and_b32_e32 v48, -8, v48
	v_sub_u32_e32 v48, v50, v48
	v_cmp_gt_i32_e64 s[14:15], 0, v48
	v_mov_b32_e32 v50, 0x61
	s_mov_b32 s4, 0x2aaaaaab
	v_cndmask_b32_e64 v50, v198, v50, s[14:15]
	v_mul_lo_u32 v48, v48, v50
	v_add_u32_e32 v48, v48, v49
	v_mul_hi_i32 v49, v48, s4
	v_lshrrev_b32_e32 v50, 31, v49
	v_ashrrev_i32_e32 v49, 3, v49
	v_add_u32_e32 v49, v49, v50
	v_lshlrev_b32_e32 v50, 3, v49
	v_sub_u32_e32 v51, 0x80, v50
	v_min_i32_e32 v51, 8, v51
	v_sub_u32_e32 v52, 0, v51
	v_max_i32_e32 v51, v51, v52
	v_cvt_f32_u32_e32 v52, v51
	v_mul_lo_u32 v49, v49, 48
	v_sub_u32_e32 v48, v48, v49
	v_sub_u32_e32 v53, 0, v48
	v_rcp_iflag_f32_e32 v52, v52
	v_ashrrev_i32_e32 v49, 31, v48
	v_max_i32_e32 v48, v48, v53
	v_sub_u32_e32 v53, 0, v51
	v_mul_f32_e32 v52, 0x4f7ffffe, v52
	v_cvt_u32_f32_e32 v52, v52
	v_mul_lo_u32 v53, v53, v52
	v_mul_hi_u32 v53, v52, v53
	v_add_u32_e32 v52, v52, v53
	v_mul_hi_u32 v52, v48, v52
	v_mul_lo_u32 v52, v52, v51
	v_sub_u32_e32 v48, v48, v52
	v_sub_u32_e32 v52, v48, v51
	v_cmp_ge_u32_e64 s[14:15], v48, v51
	s_nop 1
	v_cndmask_b32_e64 v48, v48, v52, s[14:15]
	v_sub_u32_e32 v52, v48, v51
	v_cmp_ge_u32_e64 s[14:15], v48, v51
	s_nop 1
	v_cndmask_b32_e64 v48, v48, v52, s[14:15]
	v_xor_b32_e32 v48, v48, v49
	v_sub_u32_e32 v48, v48, v49
	v_add_u32_e32 v48, v50, v48
	v_lshl_or_b32 v48, v48, 8, v81
	v_ashrrev_i32_e32 v49, 31, v48
	v_lshlrev_b64 v[48:49], 6, v[48:49]
	v_lshl_add_u64 v[60:61], s[0:1], 0, v[48:49]
	global_load_dwordx4 v[48:51], v[60:61], off offset:48
	global_load_dwordx4 v[52:55], v[60:61], off offset:32
	global_load_dwordx4 v[56:59], v[60:61], off offset:16
	s_nop 0
	global_load_dwordx4 v[60:63], v[60:61], off
;     __host__ __device__ bool next(int i, Unit& u) const {
;         const long L = (long)i * G + c; if (L >= nwg) return false;
;         int wgid = (int)L; { const int q = nwg / NXCD, r = nwg % NXCD, xcd = wgid % NXCD, off = wgid / NXCD; wgid = (xcd < r ? xcd * (q + 1) : r * (q + 1) + (xcd - r) * q) + off; }
;         const int nig = WGM * nN, gid = wgid / nig, fm = gid * WGM, gsz = (nM - fm) < WGM ? (nM - fm) : WGM;
;         u.pm = fm + ((wgid % nig) % gsz); u.pn = (wgid % nig) / gsz; return true;
; __device__ __forceinline__ void build_rstd_table(LAS unsigned char* lds, const float* ssp, const pg8::StaticOrder& S, int tid) {
;     ...
;     for (int k = 0; k < 6; ++k) { pg8::Unit u; ok[k] = S.next((tid >> 8) + 2 * k, u);
;         if (ok[k]) { const f32x4* q = (const f32x4*)(ssp + (size_t)(u.pm * 256 + (tid & 255)) * 16);
; #pragma unroll
;             for (int j = 0; j < 4; ++j) p[k][j] = q[j]; } }
.LBB0_726:
	s_or_b64 exec, exec, s[2:3]
	v_add_u32_e32 v66, 8, v80
	v_mov_b64_e32 v[64:65], s[96:97]
	v_mad_i64_i32 v[66:67], s[2:3], v66, s69, v[64:65]
	s_mov_b64 s[2:3], 0x300
	s_nop 0
	v_cmp_gt_i64_e64 s[14:15], s[2:3], v[66:67]
	s_and_saveexec_b64 s[2:3], s[14:15]
	s_cbranch_execz .LBB0_728
	v_ashrrev_i32_e32 v64, 31, v66
	v_lshrrev_b32_e32 v64, 29, v64
	v_add_u32_e32 v64, v66, v64
	v_ashrrev_i32_e32 v65, 3, v64
	v_and_b32_e32 v64, -8, v64
	v_sub_u32_e32 v64, v66, v64
	v_cmp_gt_i32_e64 s[16:17], 0, v64
	v_mov_b32_e32 v66, 0x61
	s_mov_b32 s4, 0x2aaaaaab
	v_cndmask_b32_e64 v66, v198, v66, s[16:17]
	v_mul_lo_u32 v64, v64, v66
	v_add_u32_e32 v64, v64, v65
	v_mul_hi_i32 v65, v64, s4
	v_lshrrev_b32_e32 v66, 31, v65
	v_ashrrev_i32_e32 v65, 3, v65
	v_add_u32_e32 v65, v65, v66
	v_lshlrev_b32_e32 v66, 3, v65
	v_sub_u32_e32 v67, 0x80, v66
	v_min_i32_e32 v67, 8, v67
	v_sub_u32_e32 v68, 0, v67
	v_max_i32_e32 v67, v67, v68
	v_cvt_f32_u32_e32 v68, v67
	v_mul_lo_u32 v65, v65, 48
	v_sub_u32_e32 v64, v64, v65
	v_sub_u32_e32 v69, 0, v64
	v_rcp_iflag_f32_e32 v68, v68
	v_ashrrev_i32_e32 v65, 31, v64
	v_max_i32_e32 v64, v64, v69
	v_sub_u32_e32 v69, 0, v67
	v_mul_f32_e32 v68, 0x4f7ffffe, v68
	v_cvt_u32_f32_e32 v68, v68
	v_mul_lo_u32 v69, v69, v68
	v_mul_hi_u32 v69, v68, v69
	v_add_u32_e32 v68, v68, v69
	v_mul_hi_u32 v68, v64, v68
	v_mul_lo_u32 v68, v68, v67
	v_sub_u32_e32 v64, v64, v68
	v_sub_u32_e32 v68, v64, v67
	v_cmp_ge_u32_e64 s[16:17], v64, v67
	s_nop 1
	v_cndmask_b32_e64 v64, v64, v68, s[16:17]
	v_sub_u32_e32 v68, v64, v67
	v_cmp_ge_u32_e64 s[16:17], v64, v67
	s_nop 1
	v_cndmask_b32_e64 v64, v64, v68, s[16:17]
	v_xor_b32_e32 v64, v64, v65
	v_sub_u32_e32 v64, v64, v65
	v_add_u32_e32 v64, v66, v64
	v_lshl_or_b32 v64, v64, 8, v81
	v_ashrrev_i32_e32 v65, 31, v64
	v_lshlrev_b64 v[64:65], 6, v[64:65]
	v_lshl_add_u64 v[76:77], s[0:1], 0, v[64:65]
	global_load_dwordx4 v[64:67], v[76:77], off offset:16
	global_load_dwordx4 v[72:75], v[76:77], off
	global_load_dwordx4 v[68:71], v[76:77], off offset:32
	s_nop 0
	global_load_dwordx4 v[76:79], v[76:77], off offset:48
.LBB0_728:
	s_or_b64 exec, exec, s[2:3]
	v_add_u32_e32 v80, 10, v80
	v_mov_b64_e32 v[82:83], s[96:97]
	v_mad_i64_i32 v[82:83], s[2:3], v80, s69, v[82:83]
	s_mov_b64 s[2:3], 0x300
	s_nop 0
	v_cmp_gt_i64_e64 s[16:17], s[2:3], v[82:83]
	s_and_saveexec_b64 s[2:3], s[16:17]
	s_cbranch_execz .LBB0_808
	v_ashrrev_i32_e32 v80, 31, v82
	v_lshrrev_b32_e32 v80, 29, v80
	v_add_u32_e32 v80, v82, v80
	v_ashrrev_i32_e32 v83, 3, v80
	v_and_b32_e32 v80, -8, v80
	v_sub_u32_e32 v80, v82, v80
	v_cmp_gt_i32_e64 s[18:19], 0, v80
	v_mov_b32_e32 v82, 0x61
	s_mov_b32 s4, 0x2aaaaaab
	v_cndmask_b32_e64 v82, v198, v82, s[18:19]
	v_mul_lo_u32 v80, v80, v82
	v_add_u32_e32 v80, v80, v83
	v_mul_hi_i32 v82, v80, s4
	v_lshrrev_b32_e32 v83, 31, v82
	v_ashrrev_i32_e32 v82, 3, v82
	v_add_u32_e32 v82, v82, v83
	v_lshlrev_b32_e32 v83, 3, v82
	v_sub_u32_e32 v84, 0x80, v83
	v_min_i32_e32 v84, 8, v84
	v_sub_u32_e32 v85, 0, v84
	v_max_i32_e32 v84, v84, v85
	v_cvt_f32_u32_e32 v85, v84
	v_mul_lo_u32 v82, v82, 48
	v_sub_u32_e32 v80, v80, v82
	v_sub_u32_e32 v86, 0, v80
	v_rcp_iflag_f32_e32 v85, v85
	v_ashrrev_i32_e32 v82, 31, v80
	v_max_i32_e32 v80, v80, v86
	v_sub_u32_e32 v86, 0, v84
	v_mul_f32_e32 v85, 0x4f7ffffe, v85
	v_cvt_u32_f32_e32 v85, v85
	v_mul_lo_u32 v86, v86, v85
	v_mul_hi_u32 v86, v85, v86
	v_add_u32_e32 v85, v85, v86
	v_mul_hi_u32 v85, v80, v85
	v_mul_lo_u32 v85, v85, v84
	v_sub_u32_e32 v80, v80, v85
	v_sub_u32_e32 v85, v80, v84
	v_cmp_ge_u32_e64 s[18:19], v80, v84
	s_nop 1
	v_cndmask_b32_e64 v80, v80, v85, s[18:19]
	v_sub_u32_e32 v85, v80, v84
	v_cmp_ge_u32_e64 s[18:19], v80, v84
	s_nop 1
	v_cndmask_b32_e64 v80, v80, v85, s[18:19]
	v_xor_b32_e32 v80, v80, v82
	v_sub_u32_e32 v80, v80, v82
	v_add_u32_e32 v80, v83, v80
	v_lshl_or_b32 v80, v80, 8, v81
	v_ashrrev_i32_e32 v81, 31, v80
	v_lshlrev_b64 v[80:81], 6, v[80:81]
	v_lshl_add_u64 v[92:93], s[0:1], 0, v[80:81]
	global_load_dwordx4 v[80:83], v[92:93], off
	global_load_dwordx4 v[84:87], v[92:93], off offset:16
	global_load_dwordx4 v[88:91], v[92:93], off offset:32
	s_nop 0
	global_load_dwordx4 v[92:95], v[92:93], off offset:48
	s_or_b64 exec, exec, s[2:3]
	s_and_saveexec_b64 s[0:1], vcc
	s_cbranch_execnz .LBB0_809
